# v222 with the P11 output stores on the default cache policy instead of nt
# speedup vs baseline: 1.0083x; 1.0013x over previous
.Lp11_loop:
	s_add_u32 s8, s2, 0x1000
	s_addc_u32 s9, s3, 0
	global_load_dwordx2 v[32:33], v1, s[8:9] nt
	global_load_dwordx2 v[34:35], v1, s[8:9] offset:512 nt
	global_load_dwordx2 v[36:37], v1, s[8:9] offset:1024 nt
	global_load_dwordx2 v[38:39], v1, s[8:9] offset:1536 nt
	global_load_dwordx2 v[40:41], v1, s[8:9] offset:2048 nt
	global_load_dwordx2 v[42:43], v1, s[8:9] offset:2560 nt
	global_load_dwordx2 v[44:45], v1, s[8:9] offset:3072 nt
	global_load_dwordx2 v[46:47], v1, s[8:9] offset:3584 nt
	s_waitcnt vmcnt(16)
	v_lshlrev_b32_e32 v48, 16, v16
	v_and_b32_e32 v49, 0xffff0000, v16
	v_lshlrev_b32_e32 v50, 16, v17
	v_and_b32_e32 v51, 0xffff0000, v17
	v_lshlrev_b32_e32 v52, 16, v18
	v_and_b32_e32 v53, 0xffff0000, v18
	v_lshlrev_b32_e32 v54, 16, v19
	v_and_b32_e32 v55, 0xffff0000, v19
	v_lshlrev_b32_e32 v56, 16, v20
	v_and_b32_e32 v57, 0xffff0000, v20
	v_lshlrev_b32_e32 v58, 16, v21
	v_and_b32_e32 v59, 0xffff0000, v21
	v_lshlrev_b32_e32 v60, 16, v22
	v_and_b32_e32 v61, 0xffff0000, v22
	v_lshlrev_b32_e32 v62, 16, v23
	v_and_b32_e32 v63, 0xffff0000, v23
	v_lshlrev_b32_e32 v64, 16, v24
	v_and_b32_e32 v65, 0xffff0000, v24
	v_lshlrev_b32_e32 v66, 16, v25
	v_and_b32_e32 v67, 0xffff0000, v25
	v_lshlrev_b32_e32 v68, 16, v26
	v_and_b32_e32 v69, 0xffff0000, v26
	v_lshlrev_b32_e32 v70, 16, v27
	v_and_b32_e32 v71, 0xffff0000, v27
	v_lshlrev_b32_e32 v72, 16, v28
	v_and_b32_e32 v73, 0xffff0000, v28
	v_lshlrev_b32_e32 v74, 16, v29
	v_and_b32_e32 v75, 0xffff0000, v29
	v_lshlrev_b32_e32 v76, 16, v30
	v_and_b32_e32 v77, 0xffff0000, v30
	v_lshlrev_b32_e32 v78, 16, v31
	v_and_b32_e32 v79, 0xffff0000, v31
	v_pk_mul_f32 v[80:81], v[48:49], v[48:49]
	v_pk_fma_f32 v[80:81], v[50:51], v[50:51], v[80:81]
	v_pk_fma_f32 v[80:81], v[52:53], v[52:53], v[80:81]
	v_pk_fma_f32 v[80:81], v[54:55], v[54:55], v[80:81]
	v_pk_fma_f32 v[80:81], v[56:57], v[56:57], v[80:81]
	v_pk_fma_f32 v[80:81], v[58:59], v[58:59], v[80:81]
	v_pk_fma_f32 v[80:81], v[60:61], v[60:61], v[80:81]
	v_pk_fma_f32 v[80:81], v[62:63], v[62:63], v[80:81]
	v_pk_fma_f32 v[80:81], v[64:65], v[64:65], v[80:81]
	v_pk_fma_f32 v[80:81], v[66:67], v[66:67], v[80:81]
	v_pk_fma_f32 v[80:81], v[68:69], v[68:69], v[80:81]
	v_pk_fma_f32 v[80:81], v[70:71], v[70:71], v[80:81]
	v_pk_fma_f32 v[80:81], v[72:73], v[72:73], v[80:81]
	v_pk_fma_f32 v[80:81], v[74:75], v[74:75], v[80:81]
	v_pk_fma_f32 v[80:81], v[76:77], v[76:77], v[80:81]
	v_pk_fma_f32 v[80:81], v[78:79], v[78:79], v[80:81]
	v_add_f32_e32 v82, v80, v81
	ds_bpermute_b32 v83, v6, v82
	s_waitcnt lgkmcnt(0)
	v_add_f32_e32 v82, v82, v83
	ds_bpermute_b32 v83, v7, v82
	s_waitcnt lgkmcnt(0)
	v_add_f32_e32 v82, v82, v83
	ds_bpermute_b32 v83, v8, v82
	s_waitcnt lgkmcnt(0)
	v_add_f32_e32 v82, v82, v83
	ds_bpermute_b32 v83, v9, v82
	s_waitcnt lgkmcnt(0)
	v_add_f32_e32 v82, v82, v83
	ds_bpermute_b32 v83, v10, v82
	s_waitcnt lgkmcnt(0)
	v_add_f32_e32 v82, v82, v83
	ds_bpermute_b32 v83, v11, v82
	s_waitcnt lgkmcnt(0)
	v_add_f32_e32 v82, v82, v83
	v_fmamk_f32 v82, v82, 0x3a000000, v84
	v_rsq_f32_e32 v82, v82
	s_nop 0
	v_mov_b32_e32 v83, v82
	v_pk_mul_f32 v[48:49], v[48:49], v[82:83]
	v_pk_mul_f32 v[50:51], v[50:51], v[82:83]
	v_pk_mul_f32 v[52:53], v[52:53], v[82:83]
	v_pk_mul_f32 v[54:55], v[54:55], v[82:83]
	v_pk_mul_f32 v[56:57], v[56:57], v[82:83]
	v_pk_mul_f32 v[58:59], v[58:59], v[82:83]
	v_pk_mul_f32 v[60:61], v[60:61], v[82:83]
	v_pk_mul_f32 v[62:63], v[62:63], v[82:83]
	v_pk_mul_f32 v[64:65], v[64:65], v[82:83]
	v_pk_mul_f32 v[66:67], v[66:67], v[82:83]
	v_pk_mul_f32 v[68:69], v[68:69], v[82:83]
	v_pk_mul_f32 v[70:71], v[70:71], v[82:83]
	v_pk_mul_f32 v[72:73], v[72:73], v[82:83]
	v_pk_mul_f32 v[74:75], v[74:75], v[82:83]
	v_pk_mul_f32 v[76:77], v[76:77], v[82:83]
	v_pk_mul_f32 v[78:79], v[78:79], v[82:83]
	v_pk_mul_f32 v[48:49], v[48:49], v[100:101]
	v_pk_mul_f32 v[50:51], v[50:51], v[102:103]
	v_pk_mul_f32 v[52:53], v[52:53], v[104:105]
	v_pk_mul_f32 v[54:55], v[54:55], v[106:107]
	v_pk_mul_f32 v[56:57], v[56:57], v[108:109]
	v_pk_mul_f32 v[58:59], v[58:59], v[110:111]
	v_pk_mul_f32 v[60:61], v[60:61], v[112:113]
	v_pk_mul_f32 v[62:63], v[62:63], v[114:115]
	v_pk_mul_f32 v[64:65], v[64:65], v[116:117]
	v_pk_mul_f32 v[66:67], v[66:67], v[118:119]
	v_pk_mul_f32 v[68:69], v[68:69], v[120:121]
	v_pk_mul_f32 v[70:71], v[70:71], v[122:123]
	v_pk_mul_f32 v[72:73], v[72:73], v[124:125]
	v_pk_mul_f32 v[74:75], v[74:75], v[126:127]
	v_pk_mul_f32 v[76:77], v[76:77], v[128:129]
	v_pk_mul_f32 v[78:79], v[78:79], v[130:131]
	global_store_dwordx4 v2, v[48:51], s[4:5]
	global_store_dwordx4 v2, v[52:55], s[4:5] offset:1024
	global_store_dwordx4 v2, v[56:59], s[4:5] offset:2048
	global_store_dwordx4 v2, v[60:63], s[4:5] offset:3072
	global_store_dwordx4 v3, v[64:67], s[4:5]
	global_store_dwordx4 v3, v[68:71], s[4:5] offset:1024
	global_store_dwordx4 v3, v[72:75], s[4:5] offset:2048
	global_store_dwordx4 v3, v[76:79], s[4:5] offset:3072
	s_add_u32 s2, s2, 0x2000
	s_addc_u32 s3, s3, 0
	global_load_dwordx2 v[16:17], v1, s[2:3] nt
	global_load_dwordx2 v[18:19], v1, s[2:3] offset:512 nt
	global_load_dwordx2 v[20:21], v1, s[2:3] offset:1024 nt
	global_load_dwordx2 v[22:23], v1, s[2:3] offset:1536 nt
	global_load_dwordx2 v[24:25], v1, s[2:3] offset:2048 nt
	global_load_dwordx2 v[26:27], v1, s[2:3] offset:2560 nt
	global_load_dwordx2 v[28:29], v1, s[2:3] offset:3072 nt
	global_load_dwordx2 v[30:31], v1, s[2:3] offset:3584 nt
	s_waitcnt vmcnt(16)
	s_add_u32 s10, s4, 0x2000
	s_addc_u32 s11, s5, 0
	v_lshlrev_b32_e32 v48, 16, v32
	v_and_b32_e32 v49, 0xffff0000, v32
	v_lshlrev_b32_e32 v50, 16, v33
	v_and_b32_e32 v51, 0xffff0000, v33
	v_lshlrev_b32_e32 v52, 16, v34
	v_and_b32_e32 v53, 0xffff0000, v34
	v_lshlrev_b32_e32 v54, 16, v35
	v_and_b32_e32 v55, 0xffff0000, v35
	v_lshlrev_b32_e32 v56, 16, v36
	v_and_b32_e32 v57, 0xffff0000, v36
	v_lshlrev_b32_e32 v58, 16, v37
	v_and_b32_e32 v59, 0xffff0000, v37
	v_lshlrev_b32_e32 v60, 16, v38
	v_and_b32_e32 v61, 0xffff0000, v38
	v_lshlrev_b32_e32 v62, 16, v39
	v_and_b32_e32 v63, 0xffff0000, v39
	v_lshlrev_b32_e32 v64, 16, v40
	v_and_b32_e32 v65, 0xffff0000, v40
	v_lshlrev_b32_e32 v66, 16, v41
	v_and_b32_e32 v67, 0xffff0000, v41
	v_lshlrev_b32_e32 v68, 16, v42
	v_and_b32_e32 v69, 0xffff0000, v42
	v_lshlrev_b32_e32 v70, 16, v43
	v_and_b32_e32 v71, 0xffff0000, v43
	v_lshlrev_b32_e32 v72, 16, v44
	v_and_b32_e32 v73, 0xffff0000, v44
	v_lshlrev_b32_e32 v74, 16, v45
	v_and_b32_e32 v75, 0xffff0000, v45
	v_lshlrev_b32_e32 v76, 16, v46
	v_and_b32_e32 v77, 0xffff0000, v46
	v_lshlrev_b32_e32 v78, 16, v47
	v_and_b32_e32 v79, 0xffff0000, v47
	v_pk_mul_f32 v[80:81], v[48:49], v[48:49]
	v_pk_fma_f32 v[80:81], v[50:51], v[50:51], v[80:81]
	v_pk_fma_f32 v[80:81], v[52:53], v[52:53], v[80:81]
	v_pk_fma_f32 v[80:81], v[54:55], v[54:55], v[80:81]
	v_pk_fma_f32 v[80:81], v[56:57], v[56:57], v[80:81]
	v_pk_fma_f32 v[80:81], v[58:59], v[58:59], v[80:81]
	v_pk_fma_f32 v[80:81], v[60:61], v[60:61], v[80:81]
	v_pk_fma_f32 v[80:81], v[62:63], v[62:63], v[80:81]
	v_pk_fma_f32 v[80:81], v[64:65], v[64:65], v[80:81]
	v_pk_fma_f32 v[80:81], v[66:67], v[66:67], v[80:81]
	v_pk_fma_f32 v[80:81], v[68:69], v[68:69], v[80:81]
	v_pk_fma_f32 v[80:81], v[70:71], v[70:71], v[80:81]
	v_pk_fma_f32 v[80:81], v[72:73], v[72:73], v[80:81]
	v_pk_fma_f32 v[80:81], v[74:75], v[74:75], v[80:81]
	v_pk_fma_f32 v[80:81], v[76:77], v[76:77], v[80:81]
	v_pk_fma_f32 v[80:81], v[78:79], v[78:79], v[80:81]
	v_add_f32_e32 v82, v80, v81
	ds_bpermute_b32 v83, v6, v82
	s_waitcnt lgkmcnt(0)
	v_add_f32_e32 v82, v82, v83
	ds_bpermute_b32 v83, v7, v82
	s_waitcnt lgkmcnt(0)
	v_add_f32_e32 v82, v82, v83
	ds_bpermute_b32 v83, v8, v82
	s_waitcnt lgkmcnt(0)
	v_add_f32_e32 v82, v82, v83
	ds_bpermute_b32 v83, v9, v82
	s_waitcnt lgkmcnt(0)
	v_add_f32_e32 v82, v82, v83
	ds_bpermute_b32 v83, v10, v82
	s_waitcnt lgkmcnt(0)
	v_add_f32_e32 v82, v82, v83
	ds_bpermute_b32 v83, v11, v82
	s_waitcnt lgkmcnt(0)
	v_add_f32_e32 v82, v82, v83
	v_fmamk_f32 v82, v82, 0x3a000000, v84
	v_rsq_f32_e32 v82, v82
	s_nop 0
	v_mov_b32_e32 v83, v82
	v_pk_mul_f32 v[48:49], v[48:49], v[82:83]
	v_pk_mul_f32 v[50:51], v[50:51], v[82:83]
	v_pk_mul_f32 v[52:53], v[52:53], v[82:83]
	v_pk_mul_f32 v[54:55], v[54:55], v[82:83]
	v_pk_mul_f32 v[56:57], v[56:57], v[82:83]
	v_pk_mul_f32 v[58:59], v[58:59], v[82:83]
	v_pk_mul_f32 v[60:61], v[60:61], v[82:83]
	v_pk_mul_f32 v[62:63], v[62:63], v[82:83]
	v_pk_mul_f32 v[64:65], v[64:65], v[82:83]
	v_pk_mul_f32 v[66:67], v[66:67], v[82:83]
	v_pk_mul_f32 v[68:69], v[68:69], v[82:83]
	v_pk_mul_f32 v[70:71], v[70:71], v[82:83]
	v_pk_mul_f32 v[72:73], v[72:73], v[82:83]
	v_pk_mul_f32 v[74:75], v[74:75], v[82:83]
	v_pk_mul_f32 v[76:77], v[76:77], v[82:83]
	v_pk_mul_f32 v[78:79], v[78:79], v[82:83]
	v_pk_mul_f32 v[48:49], v[48:49], v[100:101]
	v_pk_mul_f32 v[50:51], v[50:51], v[102:103]
	v_pk_mul_f32 v[52:53], v[52:53], v[104:105]
	v_pk_mul_f32 v[54:55], v[54:55], v[106:107]
	v_pk_mul_f32 v[56:57], v[56:57], v[108:109]
	v_pk_mul_f32 v[58:59], v[58:59], v[110:111]
	v_pk_mul_f32 v[60:61], v[60:61], v[112:113]
	v_pk_mul_f32 v[62:63], v[62:63], v[114:115]
	v_pk_mul_f32 v[64:65], v[64:65], v[116:117]
	v_pk_mul_f32 v[66:67], v[66:67], v[118:119]
	v_pk_mul_f32 v[68:69], v[68:69], v[120:121]
	v_pk_mul_f32 v[70:71], v[70:71], v[122:123]
	v_pk_mul_f32 v[72:73], v[72:73], v[124:125]
	v_pk_mul_f32 v[74:75], v[74:75], v[126:127]
	v_pk_mul_f32 v[76:77], v[76:77], v[128:129]
	v_pk_mul_f32 v[78:79], v[78:79], v[130:131]
	global_store_dwordx4 v2, v[48:51], s[10:11]
	global_store_dwordx4 v2, v[52:55], s[10:11] offset:1024
	global_store_dwordx4 v2, v[56:59], s[10:11] offset:2048
	global_store_dwordx4 v2, v[60:63], s[10:11] offset:3072
	global_store_dwordx4 v3, v[64:67], s[10:11]
	global_store_dwordx4 v3, v[68:71], s[10:11] offset:1024
	global_store_dwordx4 v3, v[72:75], s[10:11] offset:2048
	global_store_dwordx4 v3, v[76:79], s[10:11] offset:3072
	s_add_u32 s4, s4, 0x4000
	s_addc_u32 s5, s5, 0
	s_add_i32 s6, s6, 2
	s_cmp_lt_u32 s6, 8
	s_cbranch_scc1 .Lp11_loop
	s_endpgm
